# pair8o with the x-packer per-block s_barrier moved from before the fp6 stores to the top of the block body
# baseline (speedup 1.0000x reference)
; #define LAS __attribute__((address_space(3)))
; #define LDS_WAIT() asm volatile("s_waitcnt lgkmcnt(0)" ::: "memory")
; __device__ __forceinline__ unsigned pk2(float lo, float hi) { return cvt_pk_bf16(lo, hi); }
; #define Q4C(i) __builtin_amdgcn_fmed3f(v[i] * scale, -6.f, 6.f)
;     __device__ __forceinline__ unsigned a(const pg8::Unit& u) const { return (unsigned)u.pm * (256u * K * 2u); }
;     __device__ __forceinline__ unsigned a(const pg8::Unit& u) const { return (unsigned)u.pm * (256u * K * 2u); }
;     __device__ __forceinline__ unsigned a(const pg8::Unit& u) const { return (unsigned)u.pm * (256u * K * 2u); }
;     __device__ __forceinline__ unsigned a(const pg8::Unit& u) const { return (unsigned)u.pm * (256u * K * 2u); }
;     __device__ __forceinline__ unsigned a(const pg8::Unit& u) const { return (unsigned)u.pm * (256u * K * 2u); }
; __device__ __forceinline__ unsigned q4x8(const float (&v)[8], float scale) {
;     unsigned w = 0;
;     ...
;     w = __builtin_amdgcn_cvt_scalef32_pk_fp4_f32(w, Q4C(0), Q4C(1), 1.0f, 0); w = __builtin_amdgcn_cvt_scalef32_pk_fp4_f32(w, Q4C(2), Q4C(3), 1.0f, 1);
;     w = __builtin_amdgcn_cvt_scalef32_pk_fp4_f32(w, Q4C(4), Q4C(5), 1.0f, 2); w = __builtin_amdgcn_cvt_scalef32_pk_fp4_f32(w, Q4C(6), Q4C(7), 1.0f, 3);
;     ...
;     return w;
; }
; __device__ __forceinline__ void p0_prologue(const Frame& F) {
;     ...
; #pragma unroll
;             for (int i = 0; i < 4; ++i) {
;                 const int p8 = i * 64 + plane; const size_t e = e0 + (size_t)p8 * 8;
;                 u32x4 w; w.x = pk2(a[i][0], a[i][1]); w.y = pk2(a[i][2], a[i][3]); w.z = pk2(b[i][0], b[i][1]); w.w = pk2(b[i][2], b[i][3]);
;                 *(u32x4*)(F.XB + e) = w;
;                 const float xv[8] = {a[i][0], a[i][1], a[i][2], a[i][3], b[i][0], b[i][1], b[i][2], b[i][3]};
;                 *(unsigned*)(F.XB4 + e / 2) = q4x8(xv, X4_SCALE);
;                 LAS float* d = scr + (p8 >> 2) * 36 + (p8 & 3) * 8;
;                 *(LAS f32x4*)d = a[i]; *(LAS f32x4*)(d + 4) = b[i];
;             }
;             LDS_WAIT(); asm volatile("" ::: "memory");
.LBB0_51:
	s_barrier
	v_cvt_pk_bf16_f32 v86, v28, v29
	v_cvt_pk_bf16_f32 v87, v30, v31
	v_cvt_pk_bf16_f32 v88, v24, v25
	v_cvt_pk_bf16_f32 v89, v26, v27
	v_add_f32_e32 v33, v28, v28
	v_add_f32_e32 v69, v29, v29
	global_store_dwordx4 v[72:73], v[86:89], off offset:-2048
	v_med3_f32 v33, v33, s35, v84
	v_med3_f32 v69, v69, s35, v84
	v_mov_b32_e32 v88, 0
	v_cvt_scalef32_pk_fp4_f32 v88, v33, v69, 1.0
	v_add_f32_e32 v33, v30, v30
	v_add_f32_e32 v69, v31, v31
	v_med3_f32 v33, v33, s35, v84
	v_med3_f32 v69, v69, s35, v84
	v_cvt_scalef32_pk_fp4_f32 v88, v33, v69, 1.0 op_sel:[0,0,1,0]
	v_add_f32_e32 v33, v24, v24
	v_add_f32_e32 v69, v25, v25
	v_med3_f32 v33, v33, s35, v84
	v_med3_f32 v69, v69, s35, v84
	v_lshl_add_u64 v[90:91], s[4:5], 0, v[78:79]
	v_cvt_scalef32_pk_fp4_f32 v88, v33, v69, 1.0 op_sel:[0,0,0,1]
	v_add_f32_e32 v33, v26, v26
	v_add_f32_e32 v69, v27, v27
	v_med3_f32 v33, v33, s35, v84
	v_med3_f32 v69, v69, s35, v84
	v_lshrrev_b64 v[86:87], 1, v[90:91]
	v_cvt_scalef32_pk_fp4_f32 v88, v33, v69, 1.0 op_sel:[0,0,1,1]
	v_lshl_add_u64 v[86:87], s[52:53], 0, v[86:87]
	global_store_dword v[86:87], v88, off
	ds_write_b128 v67, v[28:31]
	ds_write_b128 v67, v[24:27] offset:16
	v_cvt_pk_bf16_f32 v24, v20, v21
	v_cvt_pk_bf16_f32 v25, v22, v23
	v_cvt_pk_bf16_f32 v26, v16, v17
	v_cvt_pk_bf16_f32 v27, v18, v19
	global_store_dwordx4 v[72:73], v[24:27], off offset:-1024
	v_lshl_add_u64 v[28:29], v[90:91], 0, s[68:69]
	v_lshl_add_u64 v[86:87], v[70:71], 0, s[4:5]
	v_add_f32_e32 v24, v20, v20
	v_add_f32_e32 v25, v21, v21
	v_med3_f32 v24, v24, s35, v84
	v_med3_f32 v25, v25, s35, v84
	v_mov_b32_e32 v26, 0
	v_cvt_scalef32_pk_fp4_f32 v26, v24, v25, 1.0
	v_add_f32_e32 v24, v22, v22
	v_add_f32_e32 v25, v23, v23
	v_med3_f32 v24, v24, s35, v84
	v_med3_f32 v25, v25, s35, v84
	v_cvt_scalef32_pk_fp4_f32 v26, v24, v25, 1.0 op_sel:[0,0,1,0]
	v_add_f32_e32 v24, v16, v16
	v_add_f32_e32 v25, v17, v17
	v_med3_f32 v24, v24, s35, v84
	v_med3_f32 v25, v25, s35, v84
	v_cvt_scalef32_pk_fp4_f32 v26, v24, v25, 1.0 op_sel:[0,0,0,1]
	v_add_f32_e32 v24, v18, v18
	v_add_f32_e32 v25, v19, v19
	v_med3_f32 v24, v24, s35, v84
	v_med3_f32 v25, v25, s35, v84
	v_cvt_scalef32_pk_fp4_f32 v26, v24, v25, 1.0 op_sel:[0,0,1,1]
	v_lshrrev_b64 v[24:25], 1, v[28:29]
	v_lshl_add_u64 v[24:25], s[52:53], 0, v[24:25]
	global_store_dword v[24:25], v26, off
	ds_write_b128 v80, v[20:23]
	ds_write_b128 v80, v[16:19] offset:16
	v_cvt_pk_bf16_f32 v16, v12, v13
	v_cvt_pk_bf16_f32 v17, v14, v15
	v_cvt_pk_bf16_f32 v18, v8, v9
	v_cvt_pk_bf16_f32 v19, v10, v11
	global_store_dwordx4 v[72:73], v[16:19], off
	v_lshl_add_u64 v[20:21], v[90:91], 0, s[70:71]
	v_mov_b32_e32 v33, v32
	v_add_f32_e32 v16, v12, v12
	v_add_f32_e32 v17, v13, v13
	v_med3_f32 v16, v16, s35, v84
	v_med3_f32 v17, v17, s35, v84
	v_mov_b32_e32 v18, 0
	v_cvt_scalef32_pk_fp4_f32 v18, v16, v17, 1.0
	v_add_f32_e32 v16, v14, v14
	v_add_f32_e32 v17, v15, v15
	v_med3_f32 v16, v16, s35, v84
	v_med3_f32 v17, v17, s35, v84
	v_cvt_scalef32_pk_fp4_f32 v18, v16, v17, 1.0 op_sel:[0,0,1,0]
	v_add_f32_e32 v16, v8, v8
	v_add_f32_e32 v17, v9, v9
	v_med3_f32 v16, v16, s35, v84
	v_med3_f32 v17, v17, s35, v84
	v_cvt_scalef32_pk_fp4_f32 v18, v16, v17, 1.0 op_sel:[0,0,0,1]
	v_add_f32_e32 v16, v10, v10
	v_add_f32_e32 v17, v11, v11
	v_med3_f32 v16, v16, s35, v84
	v_med3_f32 v17, v17, s35, v84
	v_cvt_scalef32_pk_fp4_f32 v18, v16, v17, 1.0 op_sel:[0,0,1,1]
	v_lshrrev_b64 v[16:17], 1, v[20:21]
	v_lshl_add_u64 v[16:17], s[52:53], 0, v[16:17]
	global_store_dword v[16:17], v18, off
	ds_write_b128 v81, v[12:15]
	ds_write_b128 v81, v[8:11] offset:16
	v_cvt_pk_bf16_f32 v8, v4, v5
	v_cvt_pk_bf16_f32 v9, v6, v7
	v_cvt_pk_bf16_f32 v10, v0, v1
	v_cvt_pk_bf16_f32 v11, v2, v3
	global_store_dwordx4 v[72:73], v[8:11], off offset:1024
	v_lshl_add_u64 v[12:13], v[90:91], 0, s[76:77]
	s_add_u32 s16, s16, s58
	v_add_f32_e32 v8, v4, v4
	v_add_f32_e32 v9, v5, v5
	v_med3_f32 v8, v8, s35, v84
	v_med3_f32 v9, v9, s35, v84
	v_mov_b32_e32 v10, 0
	v_cvt_scalef32_pk_fp4_f32 v10, v8, v9, 1.0
	v_add_f32_e32 v8, v6, v6
	v_add_f32_e32 v9, v7, v7
	v_med3_f32 v8, v8, s35, v84
	v_med3_f32 v9, v9, s35, v84
	v_cvt_scalef32_pk_fp4_f32 v10, v8, v9, 1.0 op_sel:[0,0,1,0]
	v_add_f32_e32 v8, v0, v0
	v_add_f32_e32 v9, v1, v1
	v_med3_f32 v8, v8, s35, v84
	v_med3_f32 v9, v9, s35, v84
	v_cvt_scalef32_pk_fp4_f32 v10, v8, v9, 1.0 op_sel:[0,0,0,1]
	v_add_f32_e32 v8, v2, v2
	v_add_f32_e32 v9, v3, v3
	v_med3_f32 v8, v8, s35, v84
	v_med3_f32 v9, v9, s35, v84
	v_cvt_scalef32_pk_fp4_f32 v10, v8, v9, 1.0 op_sel:[0,0,1,1]
	v_lshrrev_b64 v[8:9], 1, v[12:13]
	v_lshl_add_u64 v[8:9], s[52:53], 0, v[8:9]
	global_store_dword v[8:9], v10, off
	ds_write_b128 v82, v[4:7]
	ds_write_b128 v82, v[0:3] offset:16
	s_waitcnt lgkmcnt(0)
; #define LAS __attribute__((address_space(3)))
; #define LDS_WAIT() asm volatile("s_waitcnt lgkmcnt(0)" ::: "memory")
;     __device__ __forceinline__ unsigned a(const pg8::Unit& u) const { return (unsigned)u.pm * (256u * K * 2u); }
;     __device__ __forceinline__ unsigned a(const pg8::Unit& u) const { return (unsigned)u.pm * (256u * K * 2u); }
;     __device__ __forceinline__ unsigned a(const pg8::Unit& u) const { return (unsigned)u.pm * (256u * K * 2u); }
;     __device__ __forceinline__ unsigned a(const pg8::Unit& u) const { return (unsigned)u.pm * (256u * K * 2u); }
;     __device__ __forceinline__ unsigned a(const pg8::Unit& u) const { return (unsigned)u.pm * (256u * K * 2u); }
; __device__ __forceinline__ void store_fp6_group(unsigned char* dst, const float (&v)[32], float scale) {
;     f32x16v a, b;
; #pragma unroll
;     for (int i = 0; i < 16; ++i) { a[i] = __builtin_amdgcn_fmed3f(v[i] * scale, -7.5f, 7.5f); b[i] = __builtin_amdgcn_fmed3f(v[16 + i] * scale, -7.5f, 7.5f); }
;     const u32x6v p = __builtin_amdgcn_cvt_scalef32_2xpk16_fp6_f32(a, b, 1.0f);
;     *(u32x4*)dst = (u32x4){p[0], p[1], p[2], p[3]};
;     *(u32x4*)(dst + 64) = (u32x4){p[4], p[5], 0u, 0u};
; }
; __device__ __forceinline__ void p0_prologue(const Frame& F) {
;     ...
;             LDS_WAIT(); asm volatile("" ::: "memory");
;             float v[32];
; #pragma unroll
;             for (int j = 0; j < 8; ++j) { const f32x4 t = *(const LAS f32x4*)(scr + plane * 36 + j * 4); v[4 * j] = t[0]; v[4 * j + 1] = t[1]; v[4 * j + 2] = t[2]; v[4 * j + 3] = t[3]; }
;             const size_t eg = e0 + (size_t)plane * 32;
;             store_fp6_group(F.XB8 + (eg >> 7) * 128 + ((eg >> 5) & 3) * 16, v, X6_SCALE);
;             LDS_WAIT(); asm volatile("" ::: "memory");
	ds_read_b128 v[0:3], v83
	ds_read_b128 v[4:7], v83 offset:16
	ds_read_b128 v[8:11], v83 offset:32
	ds_read_b128 v[12:15], v83 offset:48
	ds_read_b128 v[16:19], v83 offset:64
	ds_read_b128 v[20:23], v83 offset:80
	ds_read_b128 v[24:27], v83 offset:96
	ds_read_b128 v[28:31], v83 offset:112
	s_waitcnt lgkmcnt(7)
	v_add_f32_e32 v0, v0, v0
	s_waitcnt lgkmcnt(3)
	v_add_f32_e32 v16, v16, v16
	v_add_f32_e32 v1, v1, v1
	v_add_f32_e32 v17, v17, v17
	v_add_f32_e32 v2, v2, v2
	v_add_f32_e32 v18, v18, v18
	v_add_f32_e32 v3, v3, v3
	v_add_f32_e32 v19, v19, v19
	v_add_f32_e32 v4, v4, v4
	s_waitcnt lgkmcnt(2)
	v_add_f32_e32 v20, v20, v20
	v_add_f32_e32 v5, v5, v5
	v_add_f32_e32 v21, v21, v21
	v_add_f32_e32 v6, v6, v6
	v_add_f32_e32 v22, v22, v22
	v_add_f32_e32 v7, v7, v7
	v_add_f32_e32 v23, v23, v23
	v_add_f32_e32 v8, v8, v8
	s_waitcnt lgkmcnt(1)
	v_add_f32_e32 v24, v24, v24
	v_add_f32_e32 v9, v9, v9
	v_add_f32_e32 v25, v25, v25
	v_add_f32_e32 v10, v10, v10
	v_add_f32_e32 v26, v26, v26
	v_add_f32_e32 v11, v11, v11
	v_add_f32_e32 v27, v27, v27
	v_add_f32_e32 v12, v12, v12
	s_waitcnt lgkmcnt(0)
	v_add_f32_e32 v28, v28, v28
	v_add_f32_e32 v13, v13, v13
	v_add_f32_e32 v29, v29, v29
	v_add_f32_e32 v14, v14, v14
	v_add_f32_e32 v30, v30, v30
	v_add_f32_e32 v15, v15, v15
	v_add_f32_e32 v31, v31, v31
	v_med3_f32 v0, v0, s3, v85
	v_med3_f32 v16, v16, s3, v85
	v_med3_f32 v1, v1, s3, v85
	v_med3_f32 v17, v17, s3, v85
	v_med3_f32 v2, v2, s3, v85
	v_med3_f32 v18, v18, s3, v85
	v_med3_f32 v3, v3, s3, v85
	v_med3_f32 v19, v19, s3, v85
	v_med3_f32 v4, v4, s3, v85
	v_med3_f32 v20, v20, s3, v85
	v_med3_f32 v5, v5, s3, v85
	v_med3_f32 v21, v21, s3, v85
	v_med3_f32 v6, v6, s3, v85
	v_med3_f32 v22, v22, s3, v85
	v_med3_f32 v7, v7, s3, v85
	v_med3_f32 v23, v23, s3, v85
	v_med3_f32 v8, v8, s3, v85
	v_med3_f32 v24, v24, s3, v85
	v_med3_f32 v9, v9, s3, v85
	v_med3_f32 v25, v25, s3, v85
	v_med3_f32 v10, v10, s3, v85
	v_med3_f32 v26, v26, s3, v85
	v_med3_f32 v11, v11, s3, v85
	v_med3_f32 v27, v27, s3, v85
	v_med3_f32 v12, v12, s3, v85
	v_med3_f32 v28, v28, s3, v85
	v_med3_f32 v13, v13, s3, v85
	v_med3_f32 v29, v29, s3, v85
	v_med3_f32 v14, v14, s3, v85
	v_med3_f32 v30, v30, s3, v85
	v_med3_f32 v15, v15, s3, v85
	v_med3_f32 v31, v31, s3, v85
	v_cvt_scalef32_2xpk16_fp6_f32 v[0:5], v[0:15], v[16:31], 1.0
	v_add_co_u32_e32 v6, vcc, s72, v86
	v_mov_b32_e32 v30, v4
	s_nop 0
	v_addc_co_u32_e32 v7, vcc, 0, v87, vcc
	v_mov_b32_e32 v31, v5
	v_mbcnt_lo_u32_b32 v8, -1, 0
	v_mbcnt_hi_u32_b32 v8, -1, v8
	v_and_b32_e32 v8, 3, v8
	v_mov_b32_e32 v9, s50
	v_bfe_u32 v15, v9, 4, 1
	v_bfe_u32 v14, v9, 7, 1
	v_bfe_u32 v12, v9, 1, 1
	v_and_b32_e32 v12, v12, v14
	v_mul_u32_u24_e32 v12, 0xfc0, v12
	v_bfe_u32 v9, v9, 3, 2
	v_and_b32_e32 v13, 1, v9
	v_sub_u32_e32 v9, 0, v9
	v_and_b32_e32 v9, 3, v9
	v_xor_b32_e32 v9, v8, v9
	v_sub_u32_e32 v9, v9, v8
	v_lshlrev_b32_e32 v10, 4, v9
	v_sub_u32_e32 v10, v10, v12
	v_ashrrev_i32_e32 v11, 31, v10
	v_lshl_add_u64 v[10:11], v[6:7], 0, v[10:11]
	global_store_dwordx4 v[10:11], v[0:3], off
	v_xor_b32_e32 v13, v14, v13
	v_lshlrev_b32_e32 v13, 5, v13
	v_lshlrev_b32_e32 v14, 18, v14
	v_sub_u32_e32 v13, v13, v14
	v_lshrrev_b32_e32 v14, 1, v8
	v_xor_b32_e32 v14, v14, v15
	v_lshl_add_u32 v13, v14, 4, v13
	v_and_b32_e32 v14, 1, v8
	v_lshl_add_u32 v13, v14, 3, v13
	v_lshlrev_b32_e32 v14, 4, v8
	v_sub_u32_e32 v12, v13, v14
	v_ashrrev_i32_e32 v13, 31, v12
	v_lshl_add_u64 v[12:13], v[6:7], 0, v[12:13]
	global_store_dwordx2 v[12:13], v[30:31], off offset:64
	s_waitcnt lgkmcnt(0)
	s_waitcnt vmcnt(17)
	v_mov_b64_e32 v[24:25], v[34:35]
	s_waitcnt vmcnt(15)
	v_mov_b64_e32 v[16:17], v[42:43]
	s_waitcnt vmcnt(12)
	v_mov_b64_e32 v[8:9], v[50:51]
	s_waitcnt vmcnt(10)
	v_mov_b64_e32 v[0:1], v[58:59]
	v_mov_b64_e32 v[28:29], v[38:39]
	v_mov_b64_e32 v[20:21], v[46:47]
	v_mov_b64_e32 v[12:13], v[54:55]
	v_mov_b64_e32 v[4:5], v[62:63]
	s_addc_u32 s17, s17, s59
	v_lshl_add_u64 v[70:71], v[70:71], 0, s[62:63]
	v_lshl_add_u64 v[78:79], v[78:79], 0, s[62:63]
	v_lshl_add_u64 v[72:73], v[72:73], 0, s[66:67]
	s_andn2_b64 vcc, exec, s[0:1]
	v_mov_b64_e32 v[26:27], v[36:37]
	v_mov_b64_e32 v[18:19], v[44:45]
	v_mov_b64_e32 v[10:11], v[52:53]
	v_mov_b64_e32 v[2:3], v[60:61]
	v_mov_b64_e32 v[30:31], v[40:41]
	v_mov_b64_e32 v[22:23], v[48:49]
	v_mov_b64_e32 v[14:15], v[56:57]
	v_mov_b64_e32 v[6:7], v[64:65]
	s_cbranch_vccz .LBB0_54
